# workgroup barrier closing each grid barrier moved behind the next GEMM phase's first four weight-stage LDS-DMA loads (waves 1-7 prefetch weights while wave 0 completes the grid protocol)
# speedup vs baseline: 1.0055x; 1.0055x over previous
; #define PG8_STAGE(bufoff, gbase) do { _Pragma("unroll") for (int _i = 0; _i < 2; ++_i) \
;         __builtin_amdgcn_global_load_lds((const unsigned*)((const char*)(gbase) + voffA[_i]), (LAS unsigned*)(lds + (bufoff) + ldsw + _i * 8192), 16, 0, 0); } while (0)
; #define PG8_WAIT_V(n) asm volatile("s_waitcnt vmcnt(" #n ")" ::: "memory")
; #define PG8_BAR __builtin_amdgcn_s_barrier()
; __device__ __forceinline__ void xcd_barrier(const XcdBarrier& b, int wave) {
;     ...
;     __syncthreads();
; template <class Epi, class Sched>
; __device__ __forceinline__ void gemm_phase(LAS unsigned char* lds, const Gemm g, const Sched& S, const Epi& E, int wid) {
;     ...
;     const char* cA = (const char*)g.A + (size_t)cur.pm * tstep; const char* cB = (const char*)g.Bt + (size_t)cur.pn * tstep;
;     PG8_STAGE(PG8_SB(0, 0), cB); PG8_STAGE(PG8_SB(0, 1), cB + hstep); PG8_STAGE(PG8_SA(0, 0), cA); PG8_STAGE(PG8_SA(0, 1), cA + hstep);
;     if (wr == 1) PG8_BAR;
;     PG8_WAIT_V(2); PG8_BAR;
;     PG8_STAGE(PG8_SB(1, 0), cB + kstep); PG8_STAGE(PG8_SA(1, 0), cA + kstep); PG8_STAGE(PG8_SB(1, 1), cB + hstep + kstep);
;     PG8_WAIT_V(6); PG8_BAR;
.LBB0_1818:
.LBB0_1819:
	s_cmp_ge_i32 s2, s24
	s_cselect_b64 s[6:7], -1, 0
	s_and_b64 s[0:1], s[6:7], s[36:37]
	s_andn2_b64 vcc, exec, s[0:1]
	v_readlane_b32 s0, v253, 27
	v_readlane_b32 s1, v253, 28
	s_nop 1
	v_cndmask_b32_e64 v0, 0, 1, s[0:1]
	v_cmp_ne_u32_e64 s[36:37], 1, v0
	s_cbranch_vccnz .LBB0_1957
	v_readlane_b32 s0, v250, 39
	v_readlane_b32 s1, v250, 40
	s_lshl_b64 s[0:1], s[0:1], 21
	v_readlane_b32 s2, v251, 44
	s_add_u32 s2, s2, s0
	v_readlane_b32 s0, v251, 45
	s_addc_u32 s8, s0, s1
	v_readlane_b32 s0, v250, 24
	v_readlane_b32 s1, v250, 25
	s_and_b64 s[0:1], s[0:1], exec
	v_readlane_b32 s0, v251, 58
	v_readlane_b32 s1, v251, 59
	s_cselect_b32 s47, s1, s71
	s_cselect_b32 s46, s0, s70
	v_readlane_b32 s0, v250, 26
	v_readlane_b32 s1, v250, 27
	s_mov_b32 s1, s5
	v_writelane_b32 v250, s0, 26
	s_xor_b32 s4, s0, 1
	s_and_b64 vcc, exec, s[36:37]
	v_writelane_b32 v250, s1, 27
	v_mbcnt_lo_u32_b32 v8, -1, 0
	v_mbcnt_hi_u32_b32 v8, -1, v8
	s_cbranch_vccnz .LBB0_1944
	v_lshlrev_b32_e32 v12, 4, v8
	v_add_u32_e32 v1, s87, v12
	v_add_u32_e32 v0, 0x2000, v1
	v_ashrrev_i32_e32 v3, 31, v0
	v_lshrrev_b32_e32 v3, 22, v3
	v_add_u32_e32 v3, v0, v3
	v_ashrrev_i32_e32 v3, 10, v3
	v_mul_i32_i24_e32 v4, 0x400, v3
	v_sub_u32_e32 v0, v0, v4
	v_lshrrev_b32_e32 v4, 4, v0
	v_bitop3_b32 v0, v4, v0, 32 bitop3:0x6c
	v_ashrrev_i32_e32 v4, 31, v0
	v_lshrrev_b32_e32 v4, 26, v4
	v_add_u32_e32 v4, v0, v4
	v_ashrrev_i32_e32 v9, 6, v4
	v_and_b32_e32 v4, 0xffc0, v4
	v_sub_u32_e32 v0, v0, v4
	v_lshrrev_b16_e32 v4, 7, v0
	v_and_b32_e32 v4, 1, v4
	v_add_u16_e32 v0, v0, v4
	v_ashrrev_i32_e32 v4, 31, v1
	v_lshrrev_b32_e32 v4, 22, v4
	v_add_u32_e32 v4, v1, v4
	v_ashrrev_i32_e32 v13, 10, v4
	v_mul_i32_i24_e32 v4, 0x400, v13
	v_sub_u32_e32 v1, v1, v4
	v_lshrrev_b32_e32 v4, 4, v1
	v_lshlrev_b32_e32 v5, 3, v3
	v_bitop3_b32 v1, v4, v1, 32 bitop3:0x6c
	v_and_b32_e32 v5, 0x1ffff0, v5
	s_waitcnt lgkmcnt(0)
	v_lshlrev_b32_e32 v6, 5, v3
	v_ashrrev_i32_e32 v4, 31, v1
	v_add_u32_e32 v5, v9, v5
	v_and_b32_e32 v10, 32, v6
	v_ashrrev_i16_sdwa v0, v220, sext(v0) dst_sel:DWORD dst_unused:UNUSED_PAD src0_sel:DWORD src1_sel:BYTE_0
	v_lshrrev_b32_e32 v4, 26, v4
	v_lshl_or_b32 v5, v5, 10, v10
	v_bfe_i32 v11, v0, 0, 16
	v_add_u32_e32 v4, v1, v4
	v_add_lshl_u32 v0, v5, v11, 1
	v_ashrrev_i32_e32 v14, 6, v4
	v_lshlrev_b32_e32 v5, 3, v13
	v_and_b32_e32 v4, 0xc0, v4
	v_and_b32_e32 v5, 0x1ffff0, v5
	v_lshlrev_b32_e32 v6, 5, v13
	v_sub_u32_e32 v1, v1, v4
	v_add_u32_e32 v5, v14, v5
	v_and_b32_e32 v15, 32, v6
	v_ashrrev_i16_sdwa v1, v220, sext(v1) dst_sel:DWORD dst_unused:UNUSED_PAD src0_sel:DWORD src1_sel:BYTE_0
	v_readlane_b32 s0, v254, 5
	v_lshl_or_b32 v5, v5, 10, v15
	v_bfe_i32 v16, v1, 0, 16
	v_readlane_b32 s1, v254, 6
	s_add_u32 s58, s2, s0
	v_add_lshl_u32 v132, v5, v16, 1
	s_addc_u32 s59, s8, s1
	s_add_i32 m0, s85, 0x10000
	v_mov_b32_e32 v133, v2
	global_load_lds_dwordx4 v132, s[58:59]
	s_add_i32 m0, s85, 0x12000
	s_add_u32 s0, s58, 0x40000
	global_load_lds_dwordx4 v0, s[58:59]
	s_addc_u32 s1, s59, 0
	s_add_i32 m0, s85, 0x14000
	s_add_i32 s9, s85, 0x2000
	global_load_lds_dwordx4 v132, s[0:1]
	s_add_i32 m0, s85, 0x16000
	s_add_i32 s10, s85, 0x4000
	global_load_lds_dwordx4 v0, s[0:1]
	s_waitcnt lgkmcnt(0)
	s_barrier
	v_readlane_b32 s0, v254, 28
	s_mov_b32 m0, s85
	v_readlane_b32 s1, v254, 29
	s_add_i32 s11, s85, 0x6000
	v_mov_b32_e32 v1, v2
	v_lshl_add_u64 v[4:5], s[58:59], 0, v[132:133]
	v_cmp_ne_u32_e64 s[38:39], 1, v218
	v_lshl_add_u64 v[6:7], s[58:59], 0, v[0:1]
	global_load_lds_dwordx4 v132, s[0:1]
	s_mov_b32 m0, s9
	s_nop 0
	global_load_lds_dwordx4 v0, s[0:1]
	v_readlane_b32 s0, v254, 30
	s_mov_b32 m0, s10
	v_readlane_b32 s1, v254, 31
	s_nop 4
	global_load_lds_dwordx4 v132, s[0:1]
	s_mov_b32 m0, s11
	s_nop 0
	global_load_lds_dwordx4 v0, s[0:1]
	v_readlane_b32 s0, v254, 48
	v_readlane_b32 s1, v254, 49
	s_andn2_b64 vcc, exec, s[0:1]
	s_cbranch_vccnz .LBB0_1823
	s_barrier

; #define PG8_STAGE(bufoff, gbase) do { _Pragma("unroll") for (int _i = 0; _i < 2; ++_i) \
;         __builtin_amdgcn_global_load_lds((const unsigned*)((const char*)(gbase) + voffA[_i]), (LAS unsigned*)(lds + (bufoff) + ldsw + _i * 8192), 16, 0, 0); } while (0)
; #define PG8_WAIT_V(n) asm volatile("s_waitcnt vmcnt(" #n ")" ::: "memory")
; #define PG8_BAR __builtin_amdgcn_s_barrier()
; __device__ __forceinline__ void xcd_barrier(const XcdBarrier& b, int wave) {
;     ...
;     __syncthreads();
; template <class Epi, class Sched>
; __device__ __forceinline__ void gemm_phase(LAS unsigned char* lds, const Gemm g, const Sched& S, const Epi& E, int wid) {
;     ...
;     const char* cA = (const char*)g.A + (size_t)cur.pm * tstep; const char* cB = (const char*)g.Bt + (size_t)cur.pn * tstep;
;     PG8_STAGE(PG8_SB(0, 0), cB); PG8_STAGE(PG8_SB(0, 1), cB + hstep); PG8_STAGE(PG8_SA(0, 0), cA); PG8_STAGE(PG8_SA(0, 1), cA + hstep);
;     if (wr == 1) PG8_BAR;
;     PG8_WAIT_V(2); PG8_BAR;
;     PG8_STAGE(PG8_SB(1, 0), cB + kstep); PG8_STAGE(PG8_SA(1, 0), cA + kstep); PG8_STAGE(PG8_SB(1, 1), cB + hstep + kstep);
;     PG8_WAIT_V(6); PG8_BAR;
.LBB0_2008:
.LBB0_2009:
	v_readlane_b32 s0, v250, 26
	s_xor_b32 s44, s0, 1
	s_cmp_ge_i32 s2, s24
	v_readlane_b32 s1, v250, 27
	s_cselect_b64 s[6:7], -1, 0
	s_and_b64 s[0:1], s[6:7], s[38:39]
	s_andn2_b64 vcc, exec, s[0:1]
	s_cbranch_vccnz .LBB0_2035
	v_readlane_b32 s0, v250, 39
	v_readlane_b32 s1, v250, 40
	s_lshl_b64 s[0:1], s[0:1], 21
	v_readlane_b32 s2, v251, 46
	s_add_u32 s2, s2, s0
	v_readlane_b32 s0, v251, 47
	s_addc_u32 s4, s0, s1
	v_readlane_b32 s0, v250, 35
	v_readlane_b32 s1, v250, 36
	s_add_u32 s42, s0, 0x8000
	s_addc_u32 s43, s1, 0
	s_add_u32 s46, s0, 0xc000
	s_mov_b32 s45, s5
	s_addc_u32 s47, s1, 0
	s_and_b64 vcc, exec, s[36:37]
	v_mbcnt_lo_u32_b32 v10, -1, 0
	v_mbcnt_hi_u32_b32 v10, -1, v10
	s_cbranch_vccnz .LBB0_2030
	v_lshl_add_u32 v1, v10, 4, s87
	v_add_u32_e32 v0, 0x2000, v1
	v_ashrrev_i32_e32 v3, 31, v0
	v_lshrrev_b32_e32 v3, 22, v3
	v_add_u32_e32 v3, v0, v3
	v_ashrrev_i32_e32 v8, 10, v3
	v_mul_i32_i24_e32 v4, 0x400, v8
	v_sub_u32_e32 v0, v0, v4
	v_lshrrev_b32_e32 v4, 4, v0
	v_bitop3_b32 v0, v4, v0, 32 bitop3:0x6c
	v_ashrrev_i32_e32 v4, 31, v0
	v_lshrrev_b32_e32 v4, 26, v4
	v_add_u32_e32 v4, v0, v4
	v_ashrrev_i32_e32 v9, 6, v4
	v_and_b32_e32 v4, 0xffc0, v4
	v_sub_u32_e32 v0, v0, v4
	v_lshrrev_b16_e32 v4, 7, v0
	v_and_b32_e32 v4, 1, v4
	v_add_u16_e32 v0, v0, v4
	v_lshlrev_b32_e32 v3, 5, v8
	v_ashrrev_i16_sdwa v0, v220, sext(v0) dst_sel:DWORD dst_unused:UNUSED_PAD src0_sel:DWORD src1_sel:BYTE_0
	v_and_b32_e32 v3, 32, v3
	v_bfe_i32 v11, v0, 0, 16
	v_add_u32_e32 v0, v3, v11
	v_lshlrev_b32_e32 v3, 3, v8
	v_and_b32_e32 v3, 0x1ffff0, v3
	v_add_lshl_u32 v3, v9, v3, 11
	v_lshl_add_u32 v0, v0, 1, v3
	v_ashrrev_i32_e32 v3, 31, v1
	v_lshrrev_b32_e32 v3, 22, v3
	v_add_u32_e32 v3, v1, v3
	v_ashrrev_i32_e32 v12, 10, v3
	v_mul_i32_i24_e32 v4, 0x400, v12
	v_sub_u32_e32 v1, v1, v4
	v_lshrrev_b32_e32 v4, 4, v1
	v_bitop3_b32 v1, v4, v1, 32 bitop3:0x6c
	v_ashrrev_i32_e32 v4, 31, v1
	v_lshrrev_b32_e32 v4, 26, v4
	v_add_u32_e32 v4, v1, v4
	v_ashrrev_i32_e32 v13, 6, v4
	v_and_b32_e32 v4, 0xc0, v4
	v_sub_u32_e32 v1, v1, v4
	v_lshlrev_b32_e32 v3, 5, v12
	v_ashrrev_i16_sdwa v1, v220, sext(v1) dst_sel:DWORD dst_unused:UNUSED_PAD src0_sel:DWORD src1_sel:BYTE_0
	v_and_b32_e32 v3, 32, v3
	v_bfe_i32 v14, v1, 0, 16
	v_add_u32_e32 v1, v3, v14
	v_lshlrev_b32_e32 v3, 3, v12
	v_and_b32_e32 v3, 0x1ffff0, v3
	v_readlane_b32 s0, v254, 5
	v_add_lshl_u32 v3, v13, v3, 11
	v_readlane_b32 s1, v254, 6
	s_add_u32 s58, s2, s0
	v_lshl_add_u32 v140, v1, 1, v3
	s_addc_u32 s59, s4, s1
	s_add_i32 m0, s85, 0x10000
	v_mov_b32_e32 v141, v2
	global_load_lds_dwordx4 v140, s[58:59]
	s_add_i32 m0, s85, 0x12000
	s_add_u32 s0, s58, 0x40000
	global_load_lds_dwordx4 v0, s[58:59]
	s_addc_u32 s1, s59, 0
	s_add_i32 m0, s85, 0x14000
	s_add_i32 s8, s85, 0x2000
	global_load_lds_dwordx4 v140, s[0:1]
	s_add_i32 m0, s85, 0x16000
	s_add_i32 s9, s85, 0x4000
	global_load_lds_dwordx4 v0, s[0:1]
	s_waitcnt lgkmcnt(0)
	s_barrier
	v_readlane_b32 s0, v254, 7
	s_mov_b32 m0, s85
	v_readlane_b32 s1, v254, 8
	s_add_i32 s10, s85, 0x6000
	v_mov_b32_e32 v1, v2
	v_lshl_add_u64 v[4:5], s[58:59], 0, v[140:141]
	v_cmp_ne_u32_e64 s[38:39], 1, v218
	s_waitcnt lgkmcnt(0)
	v_lshl_add_u64 v[6:7], s[58:59], 0, v[0:1]
	global_load_lds_dwordx4 v140, s[0:1]
	s_mov_b32 m0, s8
	s_nop 0
	global_load_lds_dwordx4 v0, s[0:1]
	v_readlane_b32 s0, v254, 9
	s_mov_b32 m0, s9
	v_readlane_b32 s1, v254, 10
	s_nop 4
	global_load_lds_dwordx4 v140, s[0:1]
	s_mov_b32 m0, s10
	s_nop 0
	global_load_lds_dwordx4 v0, s[0:1]
	v_readlane_b32 s0, v254, 48
	v_readlane_b32 s1, v254, 49
	s_andn2_b64 vcc, exec, s[0:1]
	s_cbranch_vccnz .LBB0_2013
	s_barrier

; #define PG8_STAGE(bufoff, gbase) do { _Pragma("unroll") for (int _i = 0; _i < 2; ++_i) \
;         __builtin_amdgcn_global_load_lds((const unsigned*)((const char*)(gbase) + voffA[_i]), (LAS unsigned*)(lds + (bufoff) + ldsw + _i * 8192), 16, 0, 0); } while (0)
; #define PG8_WAIT_V(n) asm volatile("s_waitcnt vmcnt(" #n ")" ::: "memory")
; #define PG8_BAR __builtin_amdgcn_s_barrier()
; __device__ __forceinline__ void xcd_barrier(const XcdBarrier& b, int wave) {
;     ...
;     __syncthreads();
; template <class Epi, class Sched>
; __device__ __forceinline__ void gemm_phase(LAS unsigned char* lds, const Gemm g, const Sched& S, const Epi& E, int wid) {
;     ...
;     const char* cA = (const char*)g.A + (size_t)cur.pm * tstep; const char* cB = (const char*)g.Bt + (size_t)cur.pn * tstep;
;     PG8_STAGE(PG8_SB(0, 0), cB); PG8_STAGE(PG8_SB(0, 1), cB + hstep); PG8_STAGE(PG8_SA(0, 0), cA); PG8_STAGE(PG8_SA(0, 1), cA + hstep);
;     if (wr == 1) PG8_BAR;
;     PG8_WAIT_V(2); PG8_BAR;
;     PG8_STAGE(PG8_SB(1, 0), cB + kstep); PG8_STAGE(PG8_SA(1, 0), cA + kstep); PG8_STAGE(PG8_SB(1, 1), cB + hstep + kstep);
;     PG8_WAIT_V(6); PG8_BAR;
.LBB0_2185:
.LBB0_2186:
	s_cmp_ge_i32 s2, s24
	s_cselect_b64 s[6:7], -1, 0
	s_and_b64 s[0:1], s[6:7], s[40:41]
	s_andn2_b64 vcc, exec, s[0:1]
	s_cbranch_vccnz .LBB0_2230
	v_readlane_b32 s10, v250, 39
	v_readlane_b32 s11, v250, 40
	s_lshl_b64 s[0:1], s[10:11], 21
	v_readlane_b32 s2, v251, 50
	s_add_u32 s2, s2, s0
	v_readlane_b32 s0, v251, 51
	s_addc_u32 s8, s0, s1
	s_lshl_b32 s4, s10, 10
	v_readlane_b32 s48, v251, 6
	s_lshl_b64 s[0:1], s[4:5], 2
	v_readlane_b32 s58, v251, 16
	v_readlane_b32 s59, v251, 17
	s_add_u32 s46, s58, s0
	v_readlane_b32 s60, v251, 18
	s_addc_u32 s47, s59, s1
	v_readlane_b32 s49, v251, 7
	v_readlane_b32 s61, v251, 19
	s_add_u32 s48, s60, s0
	s_addc_u32 s49, s61, s1
	v_readlane_b32 s0, v250, 26
	v_readlane_b32 s1, v250, 27
	s_mov_b32 s1, s5
	s_mov_b32 s45, s5
	v_writelane_b32 v250, s0, 26
	s_and_b64 vcc, exec, s[36:37]
	v_readlane_b32 s50, v251, 8
	v_readlane_b32 s51, v251, 9
	v_readlane_b32 s52, v251, 10
	v_readlane_b32 s53, v251, 11
	v_readlane_b32 s54, v251, 12
	v_readlane_b32 s55, v251, 13
	v_readlane_b32 s56, v251, 14
	v_readlane_b32 s57, v251, 15
	v_readlane_b32 s62, v251, 20
	v_readlane_b32 s63, v251, 21
	v_writelane_b32 v250, s1, 27
	v_mbcnt_lo_u32_b32 v8, -1, 0
	v_mbcnt_hi_u32_b32 v8, -1, v8
	s_cbranch_vccnz .LBB0_2223
	v_lshlrev_b32_e32 v12, 4, v8
	v_add_u32_e32 v1, s87, v12
	v_add_u32_e32 v0, 0x2000, v1
	v_ashrrev_i32_e32 v3, 31, v0
	v_lshrrev_b32_e32 v3, 22, v3
	v_add_u32_e32 v3, v0, v3
	v_ashrrev_i32_e32 v3, 10, v3
	v_mul_i32_i24_e32 v4, 0x400, v3
	v_sub_u32_e32 v0, v0, v4
	v_lshrrev_b32_e32 v4, 4, v0
	v_bitop3_b32 v0, v4, v0, 32 bitop3:0x6c
	v_ashrrev_i32_e32 v4, 31, v0
	v_lshrrev_b32_e32 v4, 26, v4
	v_add_u32_e32 v4, v0, v4
	v_ashrrev_i32_e32 v9, 6, v4
	v_and_b32_e32 v4, 0xffc0, v4
	v_sub_u32_e32 v0, v0, v4
	v_lshrrev_b16_e32 v4, 7, v0
	v_and_b32_e32 v4, 1, v4
	v_add_u16_e32 v0, v0, v4
	v_ashrrev_i32_e32 v4, 31, v1
	v_lshrrev_b32_e32 v4, 22, v4
	v_add_u32_e32 v4, v1, v4
	v_ashrrev_i32_e32 v13, 10, v4
	v_mul_i32_i24_e32 v4, 0x400, v13
	v_sub_u32_e32 v1, v1, v4
	v_lshrrev_b32_e32 v4, 4, v1
	v_lshlrev_b32_e32 v5, 3, v3
	v_bitop3_b32 v1, v4, v1, 32 bitop3:0x6c
	v_and_b32_e32 v5, 0x1ffff0, v5
	s_waitcnt lgkmcnt(0)
	v_lshlrev_b32_e32 v6, 5, v3
	v_ashrrev_i32_e32 v4, 31, v1
	v_add_u32_e32 v5, v9, v5
	v_and_b32_e32 v10, 32, v6
	v_ashrrev_i16_sdwa v0, v220, sext(v0) dst_sel:DWORD dst_unused:UNUSED_PAD src0_sel:DWORD src1_sel:BYTE_0
	v_lshrrev_b32_e32 v4, 26, v4
	v_lshl_or_b32 v5, v5, 10, v10
	v_bfe_i32 v11, v0, 0, 16
	v_add_u32_e32 v4, v1, v4
	v_add_lshl_u32 v0, v5, v11, 1
	v_ashrrev_i32_e32 v14, 6, v4
	v_lshlrev_b32_e32 v5, 3, v13
	v_and_b32_e32 v4, 0xc0, v4
	v_and_b32_e32 v5, 0x1ffff0, v5
	v_lshlrev_b32_e32 v6, 5, v13
	v_sub_u32_e32 v1, v1, v4
	v_add_u32_e32 v5, v14, v5
	v_and_b32_e32 v15, 32, v6
	v_ashrrev_i16_sdwa v1, v220, sext(v1) dst_sel:DWORD dst_unused:UNUSED_PAD src0_sel:DWORD src1_sel:BYTE_0
	v_readlane_b32 s0, v254, 5
	v_lshl_or_b32 v5, v5, 10, v15
	v_bfe_i32 v16, v1, 0, 16
	v_readlane_b32 s1, v254, 6
	s_add_u32 s62, s2, s0
	v_add_lshl_u32 v132, v5, v16, 1
	s_addc_u32 s63, s8, s1
	s_add_i32 m0, s85, 0x10000
	v_mov_b32_e32 v133, v2
	global_load_lds_dwordx4 v132, s[62:63]
	s_add_i32 m0, s85, 0x12000
	s_add_u32 s0, s62, 0x40000
	global_load_lds_dwordx4 v0, s[62:63]
	s_addc_u32 s1, s63, 0
	s_add_i32 m0, s85, 0x14000
	s_add_i32 s4, s85, 0x2000
	global_load_lds_dwordx4 v132, s[0:1]
	s_add_i32 m0, s85, 0x16000
	s_add_i32 s9, s85, 0x4000
	global_load_lds_dwordx4 v0, s[0:1]
	s_waitcnt lgkmcnt(0)
	s_barrier
	v_readlane_b32 s0, v254, 34
	s_mov_b32 m0, s85
	v_readlane_b32 s1, v254, 35
	s_add_i32 s10, s85, 0x6000
	v_mov_b32_e32 v1, v2
	v_lshl_add_u64 v[4:5], s[62:63], 0, v[132:133]
	v_cmp_ne_u32_e64 s[38:39], 1, v218
	v_lshl_add_u64 v[6:7], s[62:63], 0, v[0:1]
	global_load_lds_dwordx4 v132, s[0:1]
	s_mov_b32 m0, s4
	s_nop 0
	global_load_lds_dwordx4 v0, s[0:1]
	v_readlane_b32 s0, v254, 36
	s_mov_b32 m0, s9
	v_readlane_b32 s1, v254, 37
	s_nop 4
	global_load_lds_dwordx4 v132, s[0:1]
	s_mov_b32 m0, s10
	s_nop 0
	global_load_lds_dwordx4 v0, s[0:1]
	v_readlane_b32 s0, v254, 48
	v_readlane_b32 s1, v254, 49
	s_andn2_b64 vcc, exec, s[0:1]
	s_cbranch_vccnz .LBB0_2190
	s_barrier

; #define PG8_STAGE(bufoff, gbase) do { _Pragma("unroll") for (int _i = 0; _i < 2; ++_i) \
;         __builtin_amdgcn_global_load_lds((const unsigned*)((const char*)(gbase) + voffA[_i]), (LAS unsigned*)(lds + (bufoff) + ldsw + _i * 8192), 16, 0, 0); } while (0)
; #define PG8_WAIT_V(n) asm volatile("s_waitcnt vmcnt(" #n ")" ::: "memory")
; #define PG8_BAR __builtin_amdgcn_s_barrier()
; __device__ __forceinline__ void xcd_barrier(const XcdBarrier& b, int wave) {
;     ...
;     __syncthreads();
; template <class Epi, class Sched>
; __device__ __forceinline__ void gemm_phase(LAS unsigned char* lds, const Gemm g, const Sched& S, const Epi& E, int wid) {
;     ...
;     const char* cA = (const char*)g.A + (size_t)cur.pm * tstep; const char* cB = (const char*)g.Bt + (size_t)cur.pn * tstep;
;     PG8_STAGE(PG8_SB(0, 0), cB); PG8_STAGE(PG8_SB(0, 1), cB + hstep); PG8_STAGE(PG8_SA(0, 0), cA); PG8_STAGE(PG8_SA(0, 1), cA + hstep);
;     if (wr == 1) PG8_BAR;
;     PG8_WAIT_V(2); PG8_BAR;
;     PG8_STAGE(PG8_SB(1, 0), cB + kstep); PG8_STAGE(PG8_SA(1, 0), cA + kstep); PG8_STAGE(PG8_SB(1, 1), cB + hstep + kstep);
;     PG8_WAIT_V(6); PG8_BAR;
.LBB0_2281:
.LBB0_2282:
	s_cmp_ge_i32 s2, s24
	s_cselect_b64 s[6:7], -1, 0
	s_and_b64 s[0:1], s[6:7], s[38:39]
	s_andn2_b64 vcc, exec, s[0:1]
	s_cbranch_vccnz .LBB0_2308
	v_readlane_b32 s0, v250, 39
	v_readlane_b32 s1, v250, 40
	s_lshl_b64 s[48:49], s[0:1], 23
	v_readlane_b32 s0, v250, 26
	v_readlane_b32 s1, v250, 27
	s_mov_b32 s1, s5
	v_writelane_b32 v250, s0, 26
	v_mbcnt_lo_u32_b32 v8, -1, 0
	v_mbcnt_hi_u32_b32 v8, -1, v8
	s_nop 1
	v_writelane_b32 v250, s1, 27
	s_nop 0
	v_readlane_b32 s0, v250, 35
	v_readlane_b32 s1, v250, 36
	s_add_u32 s42, s0, 0x10000
	s_addc_u32 s43, s1, 0
	s_add_u32 s46, s0, 0x14000
	s_addc_u32 s47, s1, 0
	v_readlane_b32 s0, v253, 54
	v_readlane_b32 s1, v253, 55
	s_andn2_b64 vcc, exec, s[0:1]
	s_cbranch_vccnz .LBB0_2303
	v_lshl_add_u32 v1, v8, 4, s87
	v_add_u32_e32 v0, 0x2000, v1
	v_ashrrev_i32_e32 v3, 31, v0
	v_lshrrev_b32_e32 v3, 22, v3
	v_add_u32_e32 v3, v0, v3
	v_ashrrev_i32_e32 v9, 10, v3
	v_mul_i32_i24_e32 v4, 0x400, v9
	v_sub_u32_e32 v0, v0, v4
	v_lshrrev_b32_e32 v4, 4, v0
	v_bitop3_b32 v0, v4, v0, 32 bitop3:0x6c
	v_ashrrev_i32_e32 v4, 31, v0
	v_lshrrev_b32_e32 v4, 26, v4
	v_add_u32_e32 v4, v0, v4
	v_ashrrev_i32_e32 v10, 6, v4
	v_and_b32_e32 v4, 0xffc0, v4
	v_sub_u32_e32 v0, v0, v4
	v_lshrrev_b16_e32 v4, 7, v0
	v_and_b32_e32 v4, 1, v4
	v_add_u16_e32 v0, v0, v4
	v_lshlrev_b32_e32 v3, 5, v9
	v_ashrrev_i16_sdwa v0, v220, sext(v0) dst_sel:DWORD dst_unused:UNUSED_PAD src0_sel:DWORD src1_sel:BYTE_0
	v_and_b32_e32 v3, 32, v3
	v_bfe_i32 v11, v0, 0, 16
	v_add_u32_e32 v0, v3, v11
	v_lshlrev_b32_e32 v3, 3, v9
	v_and_b32_e32 v3, 0x1ffff0, v3
	v_add_lshl_u32 v3, v10, v3, 11
	v_lshl_add_u32 v0, v0, 1, v3
	v_ashrrev_i32_e32 v3, 31, v1
	v_lshrrev_b32_e32 v3, 22, v3
	v_add_u32_e32 v3, v1, v3
	v_ashrrev_i32_e32 v12, 10, v3
	v_mul_i32_i24_e32 v4, 0x400, v12
	v_sub_u32_e32 v1, v1, v4
	v_lshrrev_b32_e32 v4, 4, v1
	v_bitop3_b32 v1, v4, v1, 32 bitop3:0x6c
	v_ashrrev_i32_e32 v4, 31, v1
	v_lshrrev_b32_e32 v4, 26, v4
	v_add_u32_e32 v4, v1, v4
	v_ashrrev_i32_e32 v13, 6, v4
	v_and_b32_e32 v4, 0xc0, v4
	v_sub_u32_e32 v1, v1, v4
	v_lshlrev_b32_e32 v3, 5, v12
	v_ashrrev_i16_sdwa v1, v220, sext(v1) dst_sel:DWORD dst_unused:UNUSED_PAD src0_sel:DWORD src1_sel:BYTE_0
	v_readlane_b32 s0, v251, 52
	v_and_b32_e32 v3, 32, v3
	v_bfe_i32 v14, v1, 0, 16
	s_add_u32 s2, s0, s48
	v_readlane_b32 s0, v251, 53
	v_add_u32_e32 v1, v3, v14
	v_lshlrev_b32_e32 v3, 3, v12
	s_addc_u32 s4, s0, s49
	v_and_b32_e32 v3, 0x1ffff0, v3
	v_readlane_b32 s0, v254, 12
	v_add_lshl_u32 v3, v13, v3, 11
	v_readlane_b32 s1, v254, 13
	s_add_u32 s60, s2, s0
	v_lshl_add_u32 v140, v1, 1, v3
	s_addc_u32 s61, s4, s1
	s_add_i32 m0, s85, 0x10000
	v_mov_b32_e32 v141, v2
	global_load_lds_dwordx4 v140, s[60:61]
	s_add_i32 m0, s85, 0x12000
	s_add_u32 s0, s60, 0x40000
	global_load_lds_dwordx4 v0, s[60:61]
	s_addc_u32 s1, s61, 0
	s_add_i32 m0, s85, 0x14000
	s_add_i32 s8, s85, 0x2000
	global_load_lds_dwordx4 v140, s[0:1]
	s_add_i32 m0, s85, 0x16000
	s_add_i32 s9, s85, 0x4000
	global_load_lds_dwordx4 v0, s[0:1]
	s_waitcnt lgkmcnt(0)
	s_barrier
	v_readlane_b32 s0, v254, 16
	s_mov_b32 m0, s85
	v_readlane_b32 s1, v254, 17
	s_add_i32 s10, s85, 0x6000
	v_mov_b32_e32 v1, v2
	v_lshl_add_u64 v[4:5], s[60:61], 0, v[140:141]
	v_cmp_ne_u32_e64 s[38:39], 1, v218
	s_waitcnt lgkmcnt(0)
	v_lshl_add_u64 v[6:7], s[60:61], 0, v[0:1]
	global_load_lds_dwordx4 v140, s[0:1]
	s_mov_b32 m0, s8
	s_nop 0
	global_load_lds_dwordx4 v0, s[0:1]
	v_readlane_b32 s0, v254, 18
	s_mov_b32 m0, s9
	v_readlane_b32 s1, v254, 19
	s_nop 4
	global_load_lds_dwordx4 v140, s[0:1]
	s_mov_b32 m0, s10
	s_nop 0
	global_load_lds_dwordx4 v0, s[0:1]
	v_readlane_b32 s0, v254, 48
	v_readlane_b32 s1, v254, 49
	s_andn2_b64 vcc, exec, s[0:1]
	s_cbranch_vccnz .LBB0_2286
	s_barrier

; #define PG8_STAGE(bufoff, gbase) do { _Pragma("unroll") for (int _i = 0; _i < 2; ++_i) \
;         __builtin_amdgcn_global_load_lds((const unsigned*)((const char*)(gbase) + voffA[_i]), (LAS unsigned*)(lds + (bufoff) + ldsw + _i * 8192), 16, 0, 0); } while (0)
; #define PG8_WAIT_V(n) asm volatile("s_waitcnt vmcnt(" #n ")" ::: "memory")
; #define PG8_BAR __builtin_amdgcn_s_barrier()
; __device__ __forceinline__ void xcd_barrier(const XcdBarrier& b, int wave) {
;     ...
;     __syncthreads();
; template <class Epi, class Sched>
; __device__ __forceinline__ void gemm_phase(LAS unsigned char* lds, const Gemm g, const Sched& S, const Epi& E, int wid) {
;     ...
;     const char* cA = (const char*)g.A + (size_t)cur.pm * tstep; const char* cB = (const char*)g.Bt + (size_t)cur.pn * tstep;
;     PG8_STAGE(PG8_SB(0, 0), cB); PG8_STAGE(PG8_SB(0, 1), cB + hstep); PG8_STAGE(PG8_SA(0, 0), cA); PG8_STAGE(PG8_SA(0, 1), cA + hstep);
;     if (wr == 1) PG8_BAR;
;     PG8_WAIT_V(2); PG8_BAR;
;     PG8_STAGE(PG8_SB(1, 0), cB + kstep); PG8_STAGE(PG8_SA(1, 0), cA + kstep); PG8_STAGE(PG8_SB(1, 1), cB + hstep + kstep);
;     PG8_WAIT_V(6); PG8_BAR;
.LBB0_2359:
.LBB0_2360:
	s_cmp_ge_i32 s2, s24
	s_cselect_b64 s[6:7], -1, 0
	s_and_b64 s[0:1], s[6:7], s[38:39]
	s_andn2_b64 vcc, exec, s[0:1]
	s_cbranch_vccnz .LBB0_2406
	v_readlane_b32 s0, v250, 26
	v_readlane_b32 s1, v250, 27
	v_readlane_b32 s8, v250, 39
	s_mov_b32 s1, s5
	v_readlane_b32 s52, v251, 22
	v_readlane_b32 s9, v250, 40
	v_writelane_b32 v250, s0, 26
	s_lshl_b32 s4, s8, 10
	v_readlane_b32 s53, v251, 23
	v_readlane_b32 s54, v251, 24
	v_readlane_b32 s55, v251, 25
	v_readlane_b32 s56, v251, 26
	v_readlane_b32 s57, v251, 27
	s_lshl_b64 s[50:51], s[8:9], 23
	v_writelane_b32 v250, s1, 27
	s_lshl_b64 s[0:1], s[4:5], 2
	v_readlane_b32 s58, v251, 28
	v_readlane_b32 s59, v251, 29
	s_mov_b64 s[52:53], s[56:57]
	s_add_u32 s46, s52, s0
	s_mov_b64 s[54:55], s[58:59]
	s_addc_u32 s47, s53, s1
	s_add_u32 s48, s54, s0
	s_addc_u32 s49, s55, s1
	s_mov_b32 s45, s5
	s_and_b64 vcc, exec, s[36:37]
	v_readlane_b32 s60, v251, 30
	v_readlane_b32 s61, v251, 31
	v_readlane_b32 s62, v251, 32
	v_readlane_b32 s63, v251, 33
	v_readlane_b32 s64, v251, 34
	v_readlane_b32 s65, v251, 35
	v_readlane_b32 s66, v251, 36
	v_readlane_b32 s67, v251, 37
	v_mbcnt_lo_u32_b32 v3, -1, 0
	v_mbcnt_hi_u32_b32 v3, -1, v3
	s_cbranch_vccnz .LBB0_2397
	v_lshlrev_b32_e32 v12, 4, v3
	v_add_u32_e32 v1, s87, v12
	v_add_u32_e32 v0, 0x2000, v1
	v_ashrrev_i32_e32 v4, 31, v0
	v_lshrrev_b32_e32 v4, 22, v4
	v_add_u32_e32 v4, v0, v4
	v_ashrrev_i32_e32 v8, 10, v4
	v_mul_i32_i24_e32 v4, 0x400, v8
	v_sub_u32_e32 v0, v0, v4
	v_lshrrev_b32_e32 v4, 4, v0
	v_bitop3_b32 v0, v4, v0, 32 bitop3:0x6c
	v_ashrrev_i32_e32 v4, 31, v0
	v_lshrrev_b32_e32 v4, 26, v4
	v_add_u32_e32 v4, v0, v4
	v_ashrrev_i32_e32 v9, 6, v4
	v_and_b32_e32 v4, 0xffc0, v4
	v_sub_u32_e32 v0, v0, v4
	v_lshrrev_b16_e32 v4, 7, v0
	v_and_b32_e32 v4, 1, v4
	v_add_u16_e32 v0, v0, v4
	v_ashrrev_i32_e32 v4, 31, v1
	v_lshrrev_b32_e32 v4, 22, v4
	v_add_u32_e32 v4, v1, v4
	v_ashrrev_i32_e32 v13, 10, v4
	v_mul_i32_i24_e32 v4, 0x400, v13
	v_sub_u32_e32 v1, v1, v4
	v_lshrrev_b32_e32 v4, 4, v1
	v_lshlrev_b32_e32 v5, 3, v8
	v_bitop3_b32 v1, v4, v1, 32 bitop3:0x6c
	v_and_b32_e32 v5, 0x7fff0, v5
	s_waitcnt lgkmcnt(0)
	v_lshlrev_b32_e32 v6, 5, v8
	v_ashrrev_i32_e32 v4, 31, v1
	v_add_u32_e32 v5, v9, v5
	v_and_b32_e32 v10, 32, v6
	v_ashrrev_i16_sdwa v0, v220, sext(v0) dst_sel:DWORD dst_unused:UNUSED_PAD src0_sel:DWORD src1_sel:BYTE_0
	v_lshrrev_b32_e32 v4, 26, v4
	v_lshl_or_b32 v5, v5, 12, v10
	v_bfe_i32 v11, v0, 0, 16
	v_add_u32_e32 v4, v1, v4
	v_readlane_b32 s0, v251, 54
	v_add_lshl_u32 v0, v5, v11, 1
	v_ashrrev_i32_e32 v14, 6, v4
	v_lshlrev_b32_e32 v5, 3, v13
	v_and_b32_e32 v4, 0xc0, v4
	s_add_u32 s2, s0, s50
	v_readlane_b32 s0, v251, 55
	v_and_b32_e32 v5, 0x7fff0, v5
	v_lshlrev_b32_e32 v6, 5, v13
	v_sub_u32_e32 v1, v1, v4
	s_addc_u32 s4, s0, s51
	v_add_u32_e32 v5, v14, v5
	v_and_b32_e32 v15, 32, v6
	v_ashrrev_i16_sdwa v1, v220, sext(v1) dst_sel:DWORD dst_unused:UNUSED_PAD src0_sel:DWORD src1_sel:BYTE_0
	v_readlane_b32 s0, v254, 38
	v_lshl_or_b32 v5, v5, 12, v15
	v_bfe_i32 v16, v1, 0, 16
	v_readlane_b32 s1, v254, 39
	s_add_u32 s62, s2, s0
	v_add_lshl_u32 v132, v5, v16, 1
	s_addc_u32 s63, s4, s1
	s_add_i32 m0, s85, 0x10000
	v_mov_b32_e32 v133, v2
	global_load_lds_dwordx4 v132, s[62:63]
	s_add_i32 m0, s85, 0x12000
	s_add_u32 s0, s62, 0x100000
	global_load_lds_dwordx4 v0, s[62:63]
	s_addc_u32 s1, s63, 0
	s_add_i32 m0, s85, 0x14000
	s_add_i32 s8, s85, 0x2000
	global_load_lds_dwordx4 v132, s[0:1]
	s_add_i32 m0, s85, 0x16000
	s_add_i32 s9, s85, 0x4000
	global_load_lds_dwordx4 v0, s[0:1]
	s_waitcnt lgkmcnt(0)
	s_barrier
	v_readlane_b32 s0, v254, 44
	s_mov_b32 m0, s85
	v_readlane_b32 s1, v254, 45
	s_add_i32 s10, s85, 0x6000
	v_mov_b32_e32 v1, v2
	v_lshl_add_u64 v[4:5], s[62:63], 0, v[132:133]
	v_cmp_ne_u32_e64 s[38:39], 1, v218
	v_lshl_add_u64 v[6:7], s[62:63], 0, v[0:1]
	global_load_lds_dwordx4 v132, s[0:1]
	s_mov_b32 m0, s8
	s_nop 0
	global_load_lds_dwordx4 v0, s[0:1]
	v_readlane_b32 s0, v254, 46
	s_mov_b32 m0, s9
	v_readlane_b32 s1, v254, 47
	s_nop 4
	global_load_lds_dwordx4 v132, s[0:1]
	s_mov_b32 m0, s10
	s_nop 0
	global_load_lds_dwordx4 v0, s[0:1]
	v_readlane_b32 s0, v254, 48
	v_readlane_b32 s1, v254, 49
	s_andn2_b64 vcc, exec, s[0:1]
	s_cbranch_vccnz .LBB0_2364
	s_barrier
